# C-phase binary search reads the running log-forget sum from LDS (staged by the same workgroup) instead of 7 dependent global loads; on top of v28
# baseline (speedup 1.0000x reference)
; #define LAS __attribute__((address_space(3)))
; __global__ void __launch_bounds__(512, 2) hymba_fwd(Args a) {
;     ...
;             LAS float* wt = (LAS float*)lds;
;             if (lane == 63) wt[wave] = sc;
;             __syncthreads();
;             float base = sc - p[7];
; #pragma unroll
;             for (int i = 0; i < 8; ++i) if (i < wave) base += wt[i];
;             f32x4 o0, o1; o0[0] = p[0] + base; o0[1] = p[1] + base; o0[2] = p[2] + base; o0[3] = p[3] + base; o1[0] = p[4] + base; o1[1] = p[5] + base; o1[2] = p[6] + base; o1[3] = p[7] + base;
;             *(f32x4*)(dst + 8 * tid) = o0; *(f32x4*)(dst + 8 * tid + 4) = o1;
;             __syncthreads();
;             if (tid < 64) {
;                 const float c0 = dst[64 * tid]; int lo = 0, hi = tid;
;                 while (lo < hi) { const int mid = (lo + hi) >> 1; if (dst[64 * mid + 63] - c0 <= att::FOX_SKIP_NATS) hi = mid; else lo = mid + 1; }
;                 jtlo[blockIdx.x * 64 + tid] = lo;
;             }
.LBB0_199:
	v_readlane_b32 s0, v249, 10
	v_readlane_b32 s1, v249, 11
	v_pk_add_f32 v[16:17], v[10:11], v[0:1] op_sel_hi:[1,0]
	v_pk_add_f32 v[14:15], v[2:3], v[0:1] op_sel_hi:[1,0]
	v_lshl_add_u64 v[2:3], v[6:7], 2, s[0:1]
	v_cmp_gt_i32_e32 vcc, 64, v12
	v_pk_add_f32 v[10:11], v[8:9], v[0:1] op_sel_hi:[1,0]
	v_pk_add_f32 v[8:9], v[4:5], v[0:1] op_sel_hi:[1,0]
	global_store_dwordx4 v[2:3], v[14:17], off
	global_store_dwordx4 v[2:3], v[8:11], off offset:16
	v_lshlrev_b32_e32 v251, 5, v12
	ds_write_b128 v251, v[14:17] offset:1024
	ds_write_b128 v251, v[8:11] offset:1040
	s_waitcnt lgkmcnt(0)
	s_barrier
	s_and_saveexec_b64 s[2:3], vcc
	s_cbranch_execz .LBB0_205
	v_mov_b32_e32 v4, 0
	v_cmp_lt_i32_e32 vcc, 0, v12
	s_and_saveexec_b64 s[4:5], vcc
	s_cbranch_execz .LBB0_204
	s_movk_i32 s0, 0xe0
	v_mad_i64_i32 v[2:3], s[0:1], v12, s0, v[2:3]
	v_lshlrev_b32_e32 v251, 8, v12
	ds_read_b32 v0, v251 offset:1024
	v_readlane_b32 s8, v249, 10
	v_mov_b32_e32 v4, 0
	s_mov_b64 s[6:7], 0
	v_mov_b32_e32 v2, v12
	v_readlane_b32 s9, v249, 11
.LBB0_202:
	v_add_u32_e32 v3, v2, v4
	v_ashrrev_i32_e32 v3, 1, v3
	v_lshlrev_b32_e32 v6, 6, v3
	v_ashrrev_i32_e32 v7, 31, v6
	v_lshlrev_b32_e32 v6, 2, v6
	ds_read_b32 v5, v6 offset:1276
	s_mov_b32 s0, 0x42ba0000
	v_add_u32_e32 v6, 1, v3
	s_waitcnt lgkmcnt(0)
	v_sub_f32_e32 v5, v5, v0
	v_cmp_nge_f32_e32 vcc, s0, v5
	s_nop 1
	v_cndmask_b32_e32 v4, v4, v6, vcc
	v_cndmask_b32_e32 v2, v3, v2, vcc
	v_cmp_ge_i32_e32 vcc, v4, v2
	s_or_b64 s[6:7], vcc, s[6:7]
	s_andn2_b64 exec, exec, s[6:7]
	s_cbranch_execnz .LBB0_202
	s_or_b64 exec, exec, s[6:7]

; __global__ void __launch_bounds__(512, 2) hymba_fwd(Args a) {
	.amdhsa_kernel _Z9hymba_fwd4Args
		.amdhsa_group_segment_fixed_size 0
		.amdhsa_private_segment_fixed_size 0
		.amdhsa_kernarg_size 352
		.amdhsa_user_sgpr_count 2
		.amdhsa_user_sgpr_dispatch_ptr 0
		.amdhsa_user_sgpr_queue_ptr 0
		.amdhsa_user_sgpr_kernarg_segment_ptr 1
		.amdhsa_user_sgpr_dispatch_id 0
		.amdhsa_user_sgpr_kernarg_preload_length 0
		.amdhsa_user_sgpr_kernarg_preload_offset 0
		.amdhsa_user_sgpr_private_segment_size 0
		.amdhsa_uses_dynamic_stack 0
		.amdhsa_enable_private_segment 0
		.amdhsa_system_sgpr_workgroup_id_x 1
		.amdhsa_system_sgpr_workgroup_id_y 0
		.amdhsa_system_sgpr_workgroup_id_z 0
		.amdhsa_system_sgpr_workgroup_info 0
		.amdhsa_system_vgpr_workitem_id 2
		.amdhsa_next_free_vgpr 252
		.amdhsa_next_free_sgpr 100
		.amdhsa_accum_offset 252
		.amdhsa_reserve_vcc 1
		.amdhsa_float_round_mode_32 0
		.amdhsa_float_round_mode_16_64 0
		.amdhsa_float_denorm_mode_32 3
		.amdhsa_float_denorm_mode_16_64 3
		.amdhsa_dx10_clamp 1
		.amdhsa_ieee_mode 1
		.amdhsa_fp16_overflow 0
		.amdhsa_tg_split 0
		.amdhsa_exception_fp_ieee_invalid_op 0
		.amdhsa_exception_fp_denorm_src 0
		.amdhsa_exception_fp_ieee_div_zero 0
		.amdhsa_exception_fp_ieee_overflow 0
		.amdhsa_exception_fp_ieee_underflow 0
		.amdhsa_exception_fp_ieee_inexact 0
		.amdhsa_exception_int_div_zero 0
	.end_amdhsa_kernel

; __global__ void __launch_bounds__(512, 2) hymba_fwd(Args a) {
amdhsa.kernels:
  - .agpr_count:     0
    .args:
      - .offset:         0
        .size:           96
        .value_kind:     by_value
      - .offset:         96
        .size:           4
        .value_kind:     hidden_block_count_x
      - .offset:         100
        .size:           4
        .value_kind:     hidden_block_count_y
      - .offset:         104
        .size:           4
        .value_kind:     hidden_block_count_z
      - .offset:         108
        .size:           2
        .value_kind:     hidden_group_size_x
      - .offset:         110
        .size:           2
        .value_kind:     hidden_group_size_y
      - .offset:         112
        .size:           2
        .value_kind:     hidden_group_size_z
      - .offset:         114
        .size:           2
        .value_kind:     hidden_remainder_x
      - .offset:         116
        .size:           2
        .value_kind:     hidden_remainder_y
      - .offset:         118
        .size:           2
        .value_kind:     hidden_remainder_z
      - .offset:         136
        .size:           8
        .value_kind:     hidden_global_offset_x
      - .offset:         144
        .size:           8
        .value_kind:     hidden_global_offset_y
      - .offset:         152
        .size:           8
        .value_kind:     hidden_global_offset_z
      - .offset:         160
        .size:           2
        .value_kind:     hidden_grid_dims
      - .offset:         184
        .size:           8
        .value_kind:     hidden_multigrid_sync_arg
      - .offset:         216
        .size:           4
        .value_kind:     hidden_dynamic_lds_size
    .group_segment_fixed_size: 0
    .kernarg_segment_align: 8
    .kernarg_segment_size: 352
    .language:       OpenCL C
    .language_version:
      - 2
      - 0
    .max_flat_workgroup_size: 512
    .name:           _Z9hymba_fwd4Args
    .private_segment_fixed_size: 0
    .sgpr_count:     106
    .sgpr_spill_count: 167
    .symbol:         _Z9hymba_fwd4Args.kd
    .uniform_work_group_size: 1
    .uses_dynamic_stack: false
    .vgpr_count:     252
    .vgpr_spill_count: 0
    .wavefront_size: 64
